# speedup vs baseline: 1.0214x; 1.0129x over previous
; __device__ __forceinline__ int ltid() { int t = threadIdx.x; asm volatile("" : "+v"(t)); return t; }
; __device__ __forceinline__ void scan_block(const Params& p, char* smem, int bs) {
;   char* ws = p.ws;
;   const int tid = ltid(), lane = tid & 63, w = tid >> 6, fr = lane & 15, fq = lane >> 4;
;   const int bh = (bs & 7) * 2 + (bs >> 6), slice = (bs >> 3) & 7, b = bh >> 3, hh = bh & 7;
;   const char* recbase = (const char*)p.out + (size_t)bh * 256 * REC_BYTES;
;   const char* ubase = ws + OFF_RH + (size_t)bh * 256 * 16384 + ((size_t)((slice * 4 + w) * 64 + lane)) * 8;
;   const float* cdp = (const float*)(ws + OFF_CD) + bh * 256;
;   u16* oraw = (u16*)(ws + OFF_RH + 64 * MiB);
;   char* Sl = smem;
;   char* Vl = smem + 8192;
;   const int oW = REC_W + ((w * 4) * 64 + lane) * 16;
;   const int oQ = REC_QD + ((w * 4) * 64 + lane) * 16;
;   const int oA = REC_AT + ((w * 2) * 64 + lane) * 16;
;   const int oK = REC_KD + ((w * 4) * 64 + lane) * 16;
;   f32x4 S0 = {0.f, 0.f, 0.f, 0.f}, S1 = S0;
;   u32x4 fA[14], fB[14], fC[14];
;   uint2 uA, uB, uC;
;     ...
;   LOADSET(fA, uA, 0);
;   LOADSET(fB, uB, 1);
;   LOADSET(fC, uC, 2);
;   __syncthreads();
;   *(u32x4*)(Sl + (w * 64 + lane) * 16) = (u32x4){0u, 0u, 0u, 0u};
;   __syncthreads();
.LBB0_872:
	s_or_b64 exec, exec, s[0:1]
	s_cmpk_gt_u32 s2, 0x7f
	s_barrier
	s_cbranch_scc1 .LBB0_887
	v_mov_b32_e32 v214, v216
	s_lshl_b32 s0, s2, 1
	s_and_b32 s0, s0, 14
	s_lshr_b32 s1, s2, 6
	s_bfe_u32 s16, s2, 0x30003
	v_and_b32_e32 v0, 0xffffffc0, v214
	v_and_b32_e32 v2, 63, v214
	s_or_b32 s0, s0, s1
	v_lshl_add_u32 v0, s16, 8, v0
	v_ashrrev_i32_e32 v218, 6, v214
	s_mul_i32 s5, s0, 0xe00000
	v_or_b32_e32 v0, v0, v2
	v_lshlrev_b32_e32 v215, 4, v2
	s_mov_b32 s1, 0
	s_mul_hi_u32 s4, s0, 0xe00000
	s_add_u32 s10, s52, s5
	v_ashrrev_i32_e32 v1, 31, v0
	v_lshl_or_b32 v184, v218, 12, v215
	s_addc_u32 s11, s53, s4
	s_lshl_b64 s[8:9], s[0:1], 22
	s_waitcnt vmcnt(0)
	v_lshlrev_b64 v[172:173], 3, v[0:1]
	s_lshl_b32 s4, s0, 8
	v_lshl_or_b32 v0, v218, 11, v215
	v_ashrrev_i32_e32 v185, 31, v184
	v_add_u32_e32 v188, 0x8000, v0
	v_lshl_add_u64 v[0:1], s[10:11], 0, v[184:185]
	s_add_u32 s6, s86, s8
	s_mov_b64 s[12:13], 0x4000
	s_movk_i32 s50, 0x4000
	s_addc_u32 s7, s87, s9
	v_lshl_add_u64 v[2:3], v[0:1], 0, s[12:13]
	v_add_co_u32_e32 v4, vcc, s50, v0
	v_ashrrev_i32_e32 v189, 31, v188
	global_load_dwordx4 v[52:55], v[0:1], off
	global_load_dwordx4 v[48:51], v[0:1], off offset:1024
	global_load_dwordx4 v[44:47], v[0:1], off offset:2048
	global_load_dwordx4 v[40:43], v[0:1], off offset:3072
	v_lshl_add_u64 v[192:193], s[6:7], 0, v[172:173]
	v_addc_co_u32_e32 v5, vcc, 0, v1, vcc
	global_load_dwordx4 v[32:35], v[2:3], off offset:1024
	global_load_dwordx4 v[28:31], v[2:3], off offset:2048
	global_load_dwordx4 v[36:39], v[4:5], off
	global_load_dwordx4 v[20:23], v[2:3], off offset:3072
	v_lshl_add_u64 v[2:3], s[10:11], 0, v[188:189]
	s_mov_b64 s[14:15], 0xa000
	s_mov_b32 s51, 0xa000
	s_add_u32 s6, s10, 0xe000
	global_load_dwordx4 v[24:27], v[2:3], off
	global_load_dwordx4 v[16:19], v[2:3], off offset:1024
	v_lshl_add_u64 v[2:3], v[0:1], 0, s[14:15]
	v_add_co_u32_e32 v0, vcc, s51, v0
	s_addc_u32 s7, s11, 0
	s_nop 0
	v_addc_co_u32_e32 v1, vcc, 0, v1, vcc
	v_lshl_add_u64 v[56:57], s[6:7], 0, v[184:185]
	v_lshl_add_u64 v[58:59], v[56:57], 0, s[12:13]
	v_add_co_u32_e32 v60, vcc, s50, v56
	global_load_dwordx4 v[8:11], v[2:3], off offset:1024
	global_load_dwordx4 v[4:7], v[2:3], off offset:2048
	global_load_dwordx4 v[12:15], v[0:1], off
	s_nop 0
	global_load_dwordx4 v[0:3], v[2:3], off offset:3072
	s_nop 0
	global_load_dwordx2 v[194:195], v[192:193], off
	global_load_dwordx4 v[112:115], v[56:57], off
	global_load_dwordx4 v[116:119], v[56:57], off offset:1024
	global_load_dwordx4 v[108:111], v[56:57], off offset:2048
	global_load_dwordx4 v[104:107], v[56:57], off offset:3072
	v_addc_co_u32_e32 v61, vcc, 0, v57, vcc
	global_load_dwordx4 v[88:91], v[58:59], off offset:1024
	global_load_dwordx4 v[80:83], v[58:59], off offset:2048
	global_load_dwordx4 v[100:103], v[60:61], off
	global_load_dwordx4 v[76:79], v[58:59], off offset:3072
	v_lshl_add_u64 v[58:59], s[6:7], 0, v[188:189]
	global_load_dwordx4 v[84:87], v[58:59], off
	global_load_dwordx4 v[72:75], v[58:59], off offset:1024
	v_lshl_add_u64 v[58:59], v[56:57], 0, s[14:15]
	v_add_co_u32_e32 v56, vcc, s51, v56
	s_add_u32 s6, s10, 0x1c000
	s_nop 0
	v_addc_co_u32_e32 v57, vcc, 0, v57, vcc
	v_add_co_u32_e32 v92, vcc, s50, v192
	s_addc_u32 s7, s11, 0
	s_nop 0
	v_addc_co_u32_e32 v93, vcc, 0, v193, vcc
	global_load_dwordx4 v[64:67], v[58:59], off offset:1024
	global_load_dwordx4 v[60:63], v[58:59], off offset:2048
	global_load_dwordx4 v[68:71], v[56:57], off
	s_nop 0
	global_load_dwordx4 v[56:59], v[58:59], off offset:3072
	s_mov_b32 s17, 0x8000
	global_load_dwordx2 v[206:207], v[92:93], off
	v_lshl_add_u64 v[92:93], s[6:7], 0, v[184:185]
	v_lshl_add_u64 v[94:95], v[92:93], 0, s[12:13]
	v_add_co_u32_e32 v96, vcc, s50, v92
	global_load_dwordx4 v[160:163], v[92:93], off
	global_load_dwordx4 v[164:167], v[92:93], off offset:1024
	global_load_dwordx4 v[156:159], v[92:93], off offset:2048
	global_load_dwordx4 v[152:155], v[92:93], off offset:3072
	v_addc_co_u32_e32 v97, vcc, 0, v93, vcc
	global_load_dwordx4 v[144:147], v[94:95], off offset:1024
	global_load_dwordx4 v[136:139], v[94:95], off offset:2048
	global_load_dwordx4 v[148:151], v[96:97], off
	global_load_dwordx4 v[132:135], v[94:95], off offset:3072
	v_lshl_add_u64 v[94:95], s[6:7], 0, v[188:189]
	global_load_dwordx4 v[140:143], v[94:95], off
	global_load_dwordx4 v[128:131], v[94:95], off offset:1024
	v_lshl_add_u64 v[94:95], v[92:93], 0, s[14:15]
	v_add_co_u32_e32 v92, vcc, s51, v92
	v_lshlrev_b32_e32 v220, 10, v218
	s_nop 0
	v_addc_co_u32_e32 v93, vcc, 0, v93, vcc
	global_load_dwordx4 v[120:123], v[94:95], off offset:1024
	global_load_dwordx4 v[96:99], v[94:95], off offset:2048
	global_load_dwordx4 v[124:127], v[92:93], off
	s_nop 0
	global_load_dwordx4 v[92:95], v[94:95], off offset:3072
	v_add_co_u32_e32 v168, vcc, s17, v192
	v_or_b32_e32 v174, v220, v215
	s_nop 0
	v_addc_co_u32_e32 v169, vcc, 0, v193, vcc
	global_load_dwordx2 v[208:209], v[168:169], off
	v_mov_b32_e32 v168, 0
	v_mov_b32_e32 v169, v168
	v_mov_b32_e32 v170, v168
	v_mov_b32_e32 v171, v168
	s_and_b32 s17, s4, 0x700
	s_barrier
; __device__ __forceinline__ float lo_bf(unsigned u) { return __uint_as_float(u << 16); }
; __device__ __forceinline__ float hi_bf(unsigned u) { return __uint_as_float(u & 0xffff0000u); }
; #define MFMA16(a, b, c) __builtin_amdgcn_mfma_f32_16x16x32_bf16(a, b, c, 0, 0, 0)
; __device__ __forceinline__ void scan_block(const Params& p, char* smem, int bs) {
;     ...
;   auto step = [&](const int ch, u32x4 (&F)[14], uint2& U) {
;     const int par = ch & 1;
;     const float cd = cdp[ch];
;     union { u32x4 u; bf16x8 v; } cv;
;     f32x4 aw = {0.f, 0.f, 0.f, 0.f}, aq = aw;
; #pragma unroll
;     for (int s2 = 0; s2 < 4; ++s2) {
;       union { u32x4 u; bf16x8 v; } sb;
;       sb.u = *(const u32x4*)(Sl + ((par * 4 + s2) * 64 + lane) * 16);
;       cv.u = F[s2];     aw = MFMA16(cv.v, sb.v, aw);
;       cv.u = F[4 + s2]; aq = MFMA16(cv.v, sb.v, aq);
;     }
;     f32x4 vn;
;     vn[0] = lo_bf(U.x) - aw[0]; vn[1] = hi_bf(U.x) - aw[1];
;     vn[2] = lo_bf(U.y) - aw[2]; vn[3] = hi_bf(U.y) - aw[3];
;     {
;       uint2 pk; pk.x = pack2(vn[0], vn[1]); pk.y = pack2(vn[2], vn[3]);
;       *(uint2*)(Vl + ((par * 2 + (w >> 1)) * 64 + lane) * 16 + (w & 1) * 8) = pk;
;     }
;     __syncthreads();
;     bf16x8 Vb[2];
; #pragma unroll
;     for (int m = 0; m < 2; ++m) { cv.u = *(const u32x4*)(Vl + ((par * 2 + m) * 64 + lane) * 16); Vb[m] = cv.v; }
;     cv.u = F[8]; aq = MFMA16(cv.v, Vb[0], aq);
;     if (w >= 2) { cv.u = F[9]; aq = MFMA16(cv.v, Vb[1], aq); }
;     f32x4 n0 = S0 * cd, n1 = S1 * cd;
;     cv.u = F[10]; n0 = MFMA16(cv.v, Vb[0], n0);
;     cv.u = F[11]; n0 = MFMA16(cv.v, Vb[1], n0);
;     cv.u = F[12]; n1 = MFMA16(cv.v, Vb[0], n1);
;     cv.u = F[13]; n1 = MFMA16(cv.v, Vb[1], n1);
;     S0 = n0; S1 = n1;
	ds_write_b128 v174, v[168:171]
	v_lshlrev_b32_e32 v169, 9, v218
	s_add_u32 s17, s54, s17
	v_and_b32_e32 v221, 0xfffffc00, v169
	v_lshlrev_b32_e32 v169, 3, v218
	s_addc_u32 s18, s55, 0
	s_lshl_b32 s19, s16, 5
	v_and_b32_e32 v222, 8, v169
	s_add_u32 s16, s17, s19
	v_lshlrev_b32_e32 v169, 1, v214
	s_addc_u32 s17, s18, 0
	v_and_b32_e32 v170, 30, v169
	v_lshl_add_u64 v[174:175], s[16:17], 0, v[170:171]
	s_mov_b64 s[16:17], 0x8c00000
	v_lshlrev_b32_e32 v186, 4, v218
	v_lshl_add_u64 v[190:191], v[174:175], 0, s[16:17]
	s_lshl_b32 s16, s2, 23
	v_lshlrev_b32_e32 v169, 9, v214
	s_and_b32 s0, s0, 7
	v_ashrrev_i32_e32 v187, 31, v186
	s_and_b32 s16, s16, 0x2000000
	v_and_b32_e32 v169, 0x6000, v169
	s_lshl_b32 s0, s0, 8
	v_or_b32_e32 v174, s16, v169
	v_mov_b32_e32 v175, v168
	v_lshlrev_b64 v[196:197], 11, v[186:187]
	s_or_b32 s0, s0, s19
	v_lshl_add_u64 v[198:199], v[174:175], 0, v[196:197]
	v_or_b32_e32 v170, s0, v170
	s_add_u32 s18, s54, s16
	s_mov_b32 s5, s1
	v_or_b32_e32 v198, v198, v170
	v_or_b32_e32 v196, v196, v169
	v_or_b32_e32 v200, 0x8c00000, v170
	s_addc_u32 s19, s55, 0
	v_lshl_add_u64 v[170:171], s[8:9], 0, v[172:173]
	s_mov_b64 s[8:9], 0x4c0c000
	v_cmp_lt_i32_e64 s[6:7], 1, v218
	v_cmp_gt_i32_e32 vcc, 2, v218
	v_or3_b32 v223, v222, v221, v215
	s_mov_b32 s17, s1
	v_mov_b32_e32 v201, v168
	v_lshl_add_u64 v[202:203], s[18:19], 0, v[196:197]
	v_lshl_add_u64 v[204:205], v[170:171], 0, s[8:9]
	s_lshl_b64 s[18:19], s[4:5], 2
	s_mov_b32 s61, -3
	v_mov_b32_e32 v224, 0x319000
	s_mov_b32 s56, 0x2a000
	s_mov_b32 s57, 0x2e000
	s_mov_b32 s58, 0x34000
	s_mov_b64 s[20:21], 0x20000
	s_mov_b32 s59, 0x8c20000
	s_mov_b64 s[40:41], 0x40000
	s_mov_b32 s60, 0x8c40000
	s_mov_b64 s[42:43], 0x60000
	s_mov_b64 s[44:45], 0xc000
	s_mov_b64 s[46:47], s[10:11]
	v_mov_b32_e32 v169, v168
	v_mov_b32_e32 v170, v168
	v_mov_b32_e32 v171, v168
	v_mov_b32_e32 v172, v168
	v_mov_b32_e32 v173, v168
	v_mov_b32_e32 v174, v168
	s_waitcnt lgkmcnt(0)
	s_barrier
	s_add_u32 s98, s54, s18
	s_addc_u32 s99, s55, s19
	global_load_dword v240, v224, s[98:99]
	global_load_dword v242, v224, s[98:99] offset:4
	global_load_dword v244, v224, s[98:99] offset:8
	s_waitcnt vmcnt(0)
.LBB0_874:
	s_waitcnt vmcnt(40)
	s_add_i32 s63, s61, 3
	s_and_b32 s0, s63, 1
	s_add_u32 s48, s54, s18
	s_addc_u32 s49, s55, s19
	s_add_u32 s98, s54, s18
	s_addc_u32 s99, s55, s19
	s_lshl_b32 s65, s0, 12
	v_or_b32_e32 v210, s65, v215
	ds_read_b128 v[176:179], v210
	ds_read_b128 v[180:183], v210 offset:1024
	s_lshl_b32 s64, s0, 11
	v_add_u32_e32 v226, s64, v223
	s_waitcnt lgkmcnt(1)
	v_mfma_f32_16x16x32_bf16 v[52:55], v[52:55], v[176:179], 0
	s_waitcnt lgkmcnt(0)
	v_mfma_f32_16x16x32_bf16 v[48:51], v[48:51], v[180:183], v[52:55]
	s_nop 5
	ds_read_b128 v[52:55], v210 offset:2048
	ds_read_b128 v[210:213], v210 offset:3072
	s_waitcnt lgkmcnt(1)
	v_mfma_f32_16x16x32_bf16 v[46:49], v[44:47], v[52:55], v[48:51]
	v_lshlrev_b32_e32 v45, 16, v194
	v_mfma_f32_16x16x32_bf16 v[36:39], v[36:39], v[176:179], 0
	s_waitcnt lgkmcnt(0)
	v_mfma_f32_16x16x32_bf16 v[40:43], v[40:43], v[210:213], v[46:49]
	v_mfma_f32_16x16x32_bf16 v[32:35], v[32:35], v[180:183], v[36:39]
	v_mfma_f32_16x16x32_bf16 v[28:31], v[28:31], v[52:55], v[32:35]
	s_nop 5
	v_sub_f32_e32 v40, v45, v40
	v_and_b32_e32 v45, 0xffff0000, v194
	v_sub_f32_e32 v41, v45, v41
	v_lshlrev_b32_e32 v45, 16, v195
	v_sub_f32_e32 v42, v45, v42
	v_and_b32_e32 v45, 0xffff0000, v195
	v_sub_f32_e32 v43, v45, v43
	v_cvt_pk_bf16_f32 v40, v40, v41
	v_cvt_pk_bf16_f32 v41, v42, v43
	v_or_b32_e32 v36, s64, v215
	ds_write_b64 v226, v[40:41] offset:8192
	s_waitcnt lgkmcnt(0)
	s_barrier
	v_mfma_f32_16x16x32_bf16 v[32:35], v[20:23], v[210:213], v[28:31]
	s_nop 2
	ds_read_b128 v[28:31], v36 offset:8192
	ds_read_b128 v[20:23], v36 offset:9216
	s_waitcnt lgkmcnt(1)
	v_mfma_f32_16x16x32_bf16 v[180:183], v[24:27], v[28:31], v[32:35]
	s_and_saveexec_b64 s[8:9], vcc
	s_xor_b64 s[8:9], exec, s[8:9]
	s_andn2_saveexec_b64 s[8:9], s[8:9]
	s_cbranch_execz .LBB0_878
	s_waitcnt lgkmcnt(0)
	v_mfma_f32_16x16x32_bf16 v[180:183], v[16:19], v[20:23], v[180:183]
.LBB0_878:
	s_or_b64 exec, exec, s[8:9]
	v_pk_mul_f32 v[18:19], v[170:171], v[240:241] op_sel_hi:[1,0]
	v_pk_mul_f32 v[16:17], v[168:169], v[240:241] op_sel_hi:[1,0]
	s_lshl_b32 s0, s0, 2
	s_xor_b32 s0, s0, 4
	v_mfma_f32_16x16x32_bf16 v[12:15], v[12:15], v[28:31], v[16:19]
	v_add_lshl_u32 v225, s0, v218, 10
	v_lshl_add_u64 v[210:211], s[16:17], 0, v[196:197]
	s_waitcnt lgkmcnt(0)
; __device__ __forceinline__ u16 f2bf(float f) { return (u16)(pack2(f, f) & 0xffffu); }
; __device__ __forceinline__ float lo_bf(unsigned u) { return __uint_as_float(u << 16); }
; __device__ __forceinline__ float hi_bf(unsigned u) { return __uint_as_float(u & 0xffff0000u); }
; #define MFMA16(a, b, c) __builtin_amdgcn_mfma_f32_16x16x32_bf16(a, b, c, 0, 0, 0)
; __device__ __forceinline__ void scan_block(const Params& p, char* smem, int bs) {
;     ...
;   auto step = [&](const int ch, u32x4 (&F)[14], uint2& U) {
;     const int par = ch & 1;
;     const float cd = cdp[ch];
;     union { u32x4 u; bf16x8 v; } cv;
;     f32x4 aw = {0.f, 0.f, 0.f, 0.f}, aq = aw;
; #pragma unroll
;     for (int s2 = 0; s2 < 4; ++s2) {
;       union { u32x4 u; bf16x8 v; } sb;
;       sb.u = *(const u32x4*)(Sl + ((par * 4 + s2) * 64 + lane) * 16);
;       cv.u = F[s2];     aw = MFMA16(cv.v, sb.v, aw);
;       cv.u = F[4 + s2]; aq = MFMA16(cv.v, sb.v, aq);
;     }
;     f32x4 vn;
;     vn[0] = lo_bf(U.x) - aw[0]; vn[1] = hi_bf(U.x) - aw[1];
;     vn[2] = lo_bf(U.y) - aw[2]; vn[3] = hi_bf(U.y) - aw[3];
;     {
;       uint2 pk; pk.x = pack2(vn[0], vn[1]); pk.y = pack2(vn[2], vn[3]);
;       *(uint2*)(Vl + ((par * 2 + (w >> 1)) * 64 + lane) * 16 + (w & 1) * 8) = pk;
;     }
;     __syncthreads();
;     bf16x8 Vb[2];
; #pragma unroll
;     for (int m = 0; m < 2; ++m) { cv.u = *(const u32x4*)(Vl + ((par * 2 + m) * 64 + lane) * 16); Vb[m] = cv.v; }
;     cv.u = F[8]; aq = MFMA16(cv.v, Vb[0], aq);
;     if (w >= 2) { cv.u = F[9]; aq = MFMA16(cv.v, Vb[1], aq); }
;     f32x4 n0 = S0 * cd, n1 = S1 * cd;
;     cv.u = F[10]; n0 = MFMA16(cv.v, Vb[0], n0);
;     cv.u = F[11]; n0 = MFMA16(cv.v, Vb[1], n0);
;     cv.u = F[12]; n1 = MFMA16(cv.v, Vb[0], n1);
;     cv.u = F[13]; n1 = MFMA16(cv.v, Vb[1], n1);
;     S0 = n0; S1 = n1;
;     {
;       cv.v = pack8(S0, S1);
;       *(u32x4*)(Sl + (((par ^ 1) * 4 + w) * 64 + lane) * 16) = cv.u;
;     }
;     {
;       const int nx = (ch + 3 < 256) ? ch + 3 : 255;
;       LOADSET(F, U, nx);
;     }
; #pragma unroll
;     for (int jj = 0; jj < 4; ++jj) {
;       const size_t row = (size_t)b * T + ch * 64 + w * 16 + 4 * fq + jj;
;       oraw[row * 1024 + hh * 128 + slice * 16 + fr] = f2bf(aq[jj]);
;     }
;     __syncthreads();
;   };
	v_mfma_f32_16x16x32_bf16 v[176:179], v[8:11], v[20:23], v[12:15]
	v_mul_f32_e64 v10, v174, v240
	v_mul_f32_e64 v11, v175, v240
	v_pk_mul_f32 v[8:9], v[172:173], v[240:241] op_sel_hi:[1,0]
	v_lshl_add_u64 v[172:173], s[54:55], 0, v[204:205]
	v_cvt_pk_bf16_f32 v174, v180, s0
	v_mfma_f32_16x16x32_bf16 v[4:7], v[4:7], v[28:31], v[8:11]
	v_mfma_f32_16x16x32_bf16 v[168:171], v[0:3], v[20:23], v[4:7]
	s_nop 1
	v_cvt_pk_bf16_f32 v8, v176, v177
	v_cvt_pk_bf16_f32 v9, v178, v179
	v_or_b32_e32 v0, v215, v225
	s_nop 2
	v_cvt_pk_bf16_f32 v10, v168, v169
	v_cvt_pk_bf16_f32 v11, v170, v171
	ds_write_b128 v0, v[8:11]
	v_lshl_add_u64 v[0:1], s[46:47], 0, v[184:185]
	v_add_co_u32_e64 v2, s[8:9], s56, v0
	s_nop 1
	v_addc_co_u32_e64 v3, s[8:9], 0, v1, s[8:9]
	global_load_dwordx4 v[52:55], v[2:3], off
	global_load_dwordx4 v[48:51], v[2:3], off offset:1024
	global_load_dwordx4 v[44:47], v[2:3], off offset:2048
	global_load_dwordx4 v[40:43], v[2:3], off offset:3072
	v_add_co_u32_e64 v2, s[8:9], s57, v0
	s_nop 1
	v_addc_co_u32_e64 v3, s[8:9], 0, v1, s[8:9]
	global_load_dwordx4 v[36:39], v[2:3], off
	global_load_dwordx4 v[32:35], v[2:3], off offset:1024
	global_load_dwordx4 v[28:31], v[2:3], off offset:2048
	global_load_dwordx4 v[20:23], v[2:3], off offset:3072
	v_lshl_add_u64 v[2:3], s[46:47], 0, v[188:189]
	v_add_co_u32_e64 v2, s[8:9], s56, v2
	s_nop 1
	v_addc_co_u32_e64 v3, s[8:9], 0, v3, s[8:9]
	v_add_co_u32_e64 v0, s[8:9], s58, v0
	global_load_dwordx4 v[24:27], v[2:3], off
	global_load_dwordx4 v[16:19], v[2:3], off offset:1024
	v_addc_co_u32_e64 v1, s[8:9], 0, v1, s[8:9]
	global_load_dwordx4 v[12:15], v[0:1], off
	global_load_dwordx4 v[8:11], v[0:1], off offset:1024
	global_load_dwordx4 v[4:7], v[0:1], off offset:2048
	s_nop 0
	global_load_dwordx4 v[0:3], v[0:1], off offset:3072
	s_nop 0
	global_load_dwordx2 v[194:195], v[172:173], off
	global_load_dword v240, v224, s[98:99] offset:12
	v_lshl_add_u64 v[172:173], v[202:203], 0, v[200:201]
	global_store_short v[172:173], v174, off
	v_or_b32_e32 v172, 0x800, v210
	v_mov_b32_e32 v173, v211
	v_cvt_pk_bf16_f32 v174, v181, s0
	v_lshl_add_u64 v[172:173], v[190:191], 0, v[172:173]
	global_store_short v[172:173], v174, off
	v_or_b32_e32 v172, 0x1000, v210
	v_mov_b32_e32 v173, v211
	v_cvt_pk_bf16_f32 v174, v182, s0
	v_lshl_add_u64 v[172:173], v[190:191], 0, v[172:173]
	global_store_short v[172:173], v174, off
	v_cvt_pk_bf16_f32 v174, v183, s0
	s_add_i32 s0, s61, 4
	v_or_b32_e32 v172, 0x1800, v210
	v_mov_b32_e32 v173, v211
	s_and_b32 s66, s0, 1
	v_lshl_add_u64 v[172:173], v[190:191], 0, v[172:173]
	v_lshl_or_b32 v212, s66, 12, v215
	global_store_short v[172:173], v174, off
	s_waitcnt lgkmcnt(0)
	s_barrier
	s_waitcnt vmcnt(40)
	ds_read_b128 v[172:175], v212
	ds_read_b128 v[180:183], v212 offset:1024
	s_waitcnt lgkmcnt(1)
	v_mfma_f32_16x16x32_bf16 v[112:115], v[112:115], v[172:175], 0
	s_lshl_b32 s8, s66, 11
	s_waitcnt lgkmcnt(0)
	v_mfma_f32_16x16x32_bf16 v[112:115], v[116:119], v[180:183], v[112:115]
	ds_read_b128 v[116:119], v212 offset:2048
	ds_read_b128 v[230:233], v212 offset:3072
	s_waitcnt lgkmcnt(1)
	v_mfma_f32_16x16x32_bf16 v[110:113], v[108:111], v[116:119], v[112:115]
	v_mfma_f32_16x16x32_bf16 v[100:103], v[100:103], v[172:175], 0
	s_waitcnt lgkmcnt(0)
	v_mfma_f32_16x16x32_bf16 v[104:107], v[104:107], v[230:233], v[110:113]
	v_mfma_f32_16x16x32_bf16 v[88:91], v[88:91], v[180:183], v[100:103]
	s_nop 2
	v_lshlrev_b32_e32 v110, 16, v206
	v_and_b32_e32 v111, 0xffff0000, v206
	s_nop 1
	v_pk_add_f32 v[104:105], v[110:111], v[104:105] neg_lo:[0,1] neg_hi:[0,1]
	v_lshlrev_b32_e32 v110, 16, v207
	v_and_b32_e32 v111, 0xffff0000, v207
	v_mfma_f32_16x16x32_bf16 v[80:83], v[80:83], v[116:119], v[88:91]
	v_add_f32_e64 v106, v110, -v106
	v_add_f32_e64 v107, v111, -v107
	v_cvt_pk_bf16_f32 v104, v104, v105
	v_cvt_pk_bf16_f32 v105, v106, v107
	v_add_u32_e32 v100, s8, v223
	ds_write_b64 v100, v[104:105] offset:8192
	v_or_b32_e32 v100, s8, v215
	s_waitcnt lgkmcnt(0)
	s_barrier
	v_mfma_f32_16x16x32_bf16 v[88:91], v[76:79], v[230:233], v[80:83]
	s_nop 2
	ds_read_b128 v[80:83], v100 offset:8192
	ds_read_b128 v[76:79], v100 offset:9216
	s_waitcnt lgkmcnt(1)
	v_mfma_f32_16x16x32_bf16 v[180:183], v[84:87], v[80:83], v[88:91]
	s_and_saveexec_b64 s[8:9], s[6:7]
	s_cbranch_execz .LBB0_880
	s_waitcnt lgkmcnt(0)
	v_mfma_f32_16x16x32_bf16 v[180:183], v[72:75], v[76:79], v[180:183]
; __device__ __forceinline__ u16 f2bf(float f) { return (u16)(pack2(f, f) & 0xffffu); }
; __device__ __forceinline__ float lo_bf(unsigned u) { return __uint_as_float(u << 16); }
; __device__ __forceinline__ float hi_bf(unsigned u) { return __uint_as_float(u & 0xffff0000u); }
; #define MFMA16(a, b, c) __builtin_amdgcn_mfma_f32_16x16x32_bf16(a, b, c, 0, 0, 0)
; __device__ __forceinline__ void scan_block(const Params& p, char* smem, int bs) {
;     ...
;   auto step = [&](const int ch, u32x4 (&F)[14], uint2& U) {
;     const int par = ch & 1;
;     const float cd = cdp[ch];
;     union { u32x4 u; bf16x8 v; } cv;
;     f32x4 aw = {0.f, 0.f, 0.f, 0.f}, aq = aw;
; #pragma unroll
;     for (int s2 = 0; s2 < 4; ++s2) {
;       union { u32x4 u; bf16x8 v; } sb;
;       sb.u = *(const u32x4*)(Sl + ((par * 4 + s2) * 64 + lane) * 16);
;       cv.u = F[s2];     aw = MFMA16(cv.v, sb.v, aw);
;       cv.u = F[4 + s2]; aq = MFMA16(cv.v, sb.v, aq);
;     }
;     f32x4 vn;
;     vn[0] = lo_bf(U.x) - aw[0]; vn[1] = hi_bf(U.x) - aw[1];
;     vn[2] = lo_bf(U.y) - aw[2]; vn[3] = hi_bf(U.y) - aw[3];
;     {
;       uint2 pk; pk.x = pack2(vn[0], vn[1]); pk.y = pack2(vn[2], vn[3]);
;       *(uint2*)(Vl + ((par * 2 + (w >> 1)) * 64 + lane) * 16 + (w & 1) * 8) = pk;
;     }
;     __syncthreads();
;     bf16x8 Vb[2];
; #pragma unroll
;     for (int m = 0; m < 2; ++m) { cv.u = *(const u32x4*)(Vl + ((par * 2 + m) * 64 + lane) * 16); Vb[m] = cv.v; }
;     cv.u = F[8]; aq = MFMA16(cv.v, Vb[0], aq);
;     if (w >= 2) { cv.u = F[9]; aq = MFMA16(cv.v, Vb[1], aq); }
;     f32x4 n0 = S0 * cd, n1 = S1 * cd;
;     cv.u = F[10]; n0 = MFMA16(cv.v, Vb[0], n0);
;     cv.u = F[11]; n0 = MFMA16(cv.v, Vb[1], n0);
;     cv.u = F[12]; n1 = MFMA16(cv.v, Vb[0], n1);
;     cv.u = F[13]; n1 = MFMA16(cv.v, Vb[1], n1);
;     S0 = n0; S1 = n1;
;     {
;       cv.v = pack8(S0, S1);
;       *(u32x4*)(Sl + (((par ^ 1) * 4 + w) * 64 + lane) * 16) = cv.u;
;     }
;     {
;       const int nx = (ch + 3 < 256) ? ch + 3 : 255;
;       LOADSET(F, U, nx);
;     }
; #pragma unroll
;     for (int jj = 0; jj < 4; ++jj) {
;       const size_t row = (size_t)b * T + ch * 64 + w * 16 + 4 * fq + jj;
;       oraw[row * 1024 + hh * 128 + slice * 16 + fr] = f2bf(aq[jj]);
;     }
;     __syncthreads();
;   };
.LBB0_880:
	s_or_b64 exec, exec, s[8:9]
	v_pk_mul_f32 v[74:75], v[178:179], v[242:243] op_sel_hi:[1,0]
	v_pk_mul_f32 v[72:73], v[176:177], v[242:243] op_sel_hi:[1,0]
	s_min_u32 s0, s0, 0xfc
	s_lshl_b32 s8, s66, 2
	v_mfma_f32_16x16x32_bf16 v[68:71], v[68:71], v[80:83], v[72:75]
	s_add_i32 s0, s0, 3
	v_lshl_add_u64 v[212:213], s[54:55], 0, v[198:199]
	v_add_u32_e32 v227, s65, v215
	s_waitcnt lgkmcnt(0)
	v_mfma_f32_16x16x32_bf16 v[172:175], v[64:67], v[76:79], v[68:71]
	v_mul_f32_e64 v66, v170, v242
	v_mul_f32_e64 v67, v171, v242
	v_pk_mul_f32 v[64:65], v[168:169], v[242:243] op_sel_hi:[1,0]
	s_nop 1
	v_mfma_f32_16x16x32_bf16 v[60:63], v[60:63], v[80:83], v[64:67]
	v_mfma_f32_16x16x32_bf16 v[168:171], v[56:59], v[76:79], v[60:63]
	v_xad_u32 v56, s8, 4, v218
	s_mul_i32 s8, s0, 0xe000
	s_add_u32 s66, s10, s8
	v_cvt_pk_bf16_f32 v64, v172, v173
	v_cvt_pk_bf16_f32 v65, v174, v175
	s_nop 2
	v_cvt_pk_bf16_f32 v66, v168, v169
	v_cvt_pk_bf16_f32 v67, v170, v171
	v_lshl_or_b32 v56, v56, 10, v215
	s_addc_u32 s67, s11, 0
	ds_write_b128 v56, v[64:67]
	v_lshl_add_u64 v[56:57], s[66:67], 0, v[184:185]
	v_lshl_add_u64 v[58:59], v[56:57], 0, s[12:13]
	v_add_co_u32_e64 v60, s[8:9], s50, v56
	global_load_dwordx4 v[112:115], v[56:57], off
	global_load_dwordx4 v[116:119], v[56:57], off offset:1024
	global_load_dwordx4 v[108:111], v[56:57], off offset:2048
	global_load_dwordx4 v[104:107], v[56:57], off offset:3072
	v_addc_co_u32_e64 v61, s[8:9], 0, v57, s[8:9]
	global_load_dwordx4 v[88:91], v[58:59], off offset:1024
	global_load_dwordx4 v[80:83], v[58:59], off offset:2048
	global_load_dwordx4 v[100:103], v[60:61], off
	global_load_dwordx4 v[76:79], v[58:59], off offset:3072
	v_lshl_add_u64 v[58:59], s[66:67], 0, v[188:189]
	global_load_dwordx4 v[84:87], v[58:59], off
	global_load_dwordx4 v[72:75], v[58:59], off offset:1024
	v_lshl_add_u64 v[58:59], v[56:57], 0, s[14:15]
	v_add_co_u32_e64 v56, s[8:9], s51, v56
	s_lshl_b32 s0, s0, 14
	s_nop 0
	v_addc_co_u32_e64 v57, s[8:9], 0, v57, s[8:9]
	v_lshl_add_u64 v[176:177], v[192:193], 0, s[0:1]
	v_add_co_u32_e64 v178, s[8:9], s59, v212
	global_load_dwordx4 v[64:67], v[58:59], off offset:1024
	global_load_dwordx4 v[60:63], v[58:59], off offset:2048
	global_load_dwordx4 v[68:71], v[56:57], off
	s_nop 0
	global_load_dwordx4 v[56:59], v[58:59], off offset:3072
	v_cvt_pk_bf16_f32 v180, v180, s0
	global_load_dwordx2 v[206:207], v[176:177], off
	global_load_dword v242, v224, s[98:99] offset:16
	v_lshl_add_u64 v[176:177], v[210:211], 0, s[20:21]
	v_addc_co_u32_e64 v179, s[8:9], 0, v213, s[8:9]
	global_store_short v[178:179], v180, off
	v_or_b32_e32 v178, 0x800, v176
	v_mov_b32_e32 v179, v177
	v_cvt_pk_bf16_f32 v180, v181, s0
	v_lshl_add_u64 v[178:179], v[190:191], 0, v[178:179]
	global_store_short v[178:179], v180, off
	v_or_b32_e32 v178, 0x1000, v176
	v_mov_b32_e32 v179, v177
	v_cvt_pk_bf16_f32 v180, v182, s0
	v_lshl_add_u64 v[178:179], v[190:191], 0, v[178:179]
	v_or_b32_e32 v176, 0x1800, v176
	global_store_short v[178:179], v180, off
	v_cvt_pk_bf16_f32 v178, v183, s0
	v_lshl_add_u64 v[176:177], v[190:191], 0, v[176:177]
	global_store_short v[176:177], v178, off
	s_waitcnt lgkmcnt(0)
	s_barrier
	s_waitcnt vmcnt(40)
	ds_read_b128 v[176:179], v227
	ds_read_b128 v[180:183], v227 offset:1024
	s_waitcnt lgkmcnt(1)
	v_mfma_f32_16x16x32_bf16 v[160:163], v[160:163], v[176:179], 0
	s_waitcnt lgkmcnt(0)
	v_mfma_f32_16x16x32_bf16 v[160:163], v[164:167], v[180:183], v[160:163]
	ds_read_b128 v[164:167], v227 offset:2048
	ds_read_b128 v[230:233], v227 offset:3072
	s_waitcnt lgkmcnt(1)
	v_mfma_f32_16x16x32_bf16 v[158:161], v[156:159], v[164:167], v[160:163]
	v_mfma_f32_16x16x32_bf16 v[148:151], v[148:151], v[176:179], 0
	v_mfma_f32_16x16x32_bf16 v[144:147], v[144:147], v[180:183], v[148:151]
	s_waitcnt lgkmcnt(0)
	v_mfma_f32_16x16x32_bf16 v[152:155], v[152:155], v[230:233], v[158:161]
	s_nop 4
	v_add_u32_e32 v148, s64, v215
	v_lshlrev_b32_e32 v158, 16, v208
	v_and_b32_e32 v159, 0xffff0000, v208
	v_mfma_f32_16x16x32_bf16 v[136:139], v[136:139], v[164:167], v[144:147]
	v_add_f32_e64 v152, v158, -v152
	v_add_f32_e64 v153, v159, -v153
	v_lshlrev_b32_e32 v158, 16, v209
	v_and_b32_e32 v159, 0xffff0000, v209
	v_pk_add_f32 v[154:155], v[158:159], v[154:155] neg_lo:[0,1] neg_hi:[0,1]
	v_cvt_pk_bf16_f32 v152, v152, v153
	v_cvt_pk_bf16_f32 v153, v154, v155
	ds_write_b64 v226, v[152:153] offset:8192
	s_waitcnt lgkmcnt(0)
	s_barrier
	v_mfma_f32_16x16x32_bf16 v[144:147], v[132:135], v[230:233], v[136:139]
	s_nop 2
	ds_read_b128 v[136:139], v148 offset:8192
	ds_read_b128 v[132:135], v148 offset:9216
	s_waitcnt lgkmcnt(1)
	v_mfma_f32_16x16x32_bf16 v[176:179], v[140:143], v[136:139], v[144:147]
	s_and_saveexec_b64 s[8:9], s[6:7]
	s_cbranch_execz .LBB0_882
	s_waitcnt lgkmcnt(0)
	v_mfma_f32_16x16x32_bf16 v[176:179], v[128:131], v[132:135], v[176:179]
; __device__ __forceinline__ u16 f2bf(float f) { return (u16)(pack2(f, f) & 0xffffu); }
; __device__ __forceinline__ float lo_bf(unsigned u) { return __uint_as_float(u << 16); }
; __device__ __forceinline__ float hi_bf(unsigned u) { return __uint_as_float(u & 0xffff0000u); }
; __device__ __forceinline__ void scan_block(const Params& p, char* smem, int bs) {
;     ...
;   auto step = [&](const int ch, u32x4 (&F)[14], uint2& U) {
;     const int par = ch & 1;
;     const float cd = cdp[ch];
;     union { u32x4 u; bf16x8 v; } cv;
;     f32x4 aw = {0.f, 0.f, 0.f, 0.f}, aq = aw;
; #pragma unroll
;     for (int s2 = 0; s2 < 4; ++s2) {
;       union { u32x4 u; bf16x8 v; } sb;
;       sb.u = *(const u32x4*)(Sl + ((par * 4 + s2) * 64 + lane) * 16);
;       cv.u = F[s2];     aw = MFMA16(cv.v, sb.v, aw);
;       cv.u = F[4 + s2]; aq = MFMA16(cv.v, sb.v, aq);
;     }
;     f32x4 vn;
;     vn[0] = lo_bf(U.x) - aw[0]; vn[1] = hi_bf(U.x) - aw[1];
;     vn[2] = lo_bf(U.y) - aw[2]; vn[3] = hi_bf(U.y) - aw[3];
;     {
;       uint2 pk; pk.x = pack2(vn[0], vn[1]); pk.y = pack2(vn[2], vn[3]);
;       *(uint2*)(Vl + ((par * 2 + (w >> 1)) * 64 + lane) * 16 + (w & 1) * 8) = pk;
;     }
;     __syncthreads();
;     bf16x8 Vb[2];
; #pragma unroll
;     for (int m = 0; m < 2; ++m) { cv.u = *(const u32x4*)(Vl + ((par * 2 + m) * 64 + lane) * 16); Vb[m] = cv.v; }
;     cv.u = F[8]; aq = MFMA16(cv.v, Vb[0], aq);
;     if (w >= 2) { cv.u = F[9]; aq = MFMA16(cv.v, Vb[1], aq); }
;     f32x4 n0 = S0 * cd, n1 = S1 * cd;
;     cv.u = F[10]; n0 = MFMA16(cv.v, Vb[0], n0);
;     cv.u = F[11]; n0 = MFMA16(cv.v, Vb[1], n0);
;     cv.u = F[12]; n1 = MFMA16(cv.v, Vb[0], n1);
;     cv.u = F[13]; n1 = MFMA16(cv.v, Vb[1], n1);
;     S0 = n0; S1 = n1;
;     {
;       cv.v = pack8(S0, S1);
;       *(u32x4*)(Sl + (((par ^ 1) * 4 + w) * 64 + lane) * 16) = cv.u;
;     }
;     {
;       const int nx = (ch + 3 < 256) ? ch + 3 : 255;
;       LOADSET(F, U, nx);
;     }
; #pragma unroll
;     for (int jj = 0; jj < 4; ++jj) {
;       const size_t row = (size_t)b * T + ch * 64 + w * 16 + 4 * fq + jj;
;       oraw[row * 1024 + hh * 128 + slice * 16 + fr] = f2bf(aq[jj]);
;     }
;     __syncthreads();
;   };
; #pragma unroll 1
;   for (int ch = 0; ch < 255; ch += 3) {
;     step(ch, fA, uA);
;     step(ch + 1, fB, uB);
;     step(ch + 2, fC, uC);
;   }
;   step(255, fA, uA);
.LBB0_882:
	s_or_b64 exec, exec, s[8:9]
	s_add_i32 s0, s61, 5
	v_pk_mul_f32 v[130:131], v[174:175], v[244:245] op_sel_hi:[1,0]
	v_pk_mul_f32 v[128:129], v[172:173], v[244:245] op_sel_hi:[1,0]
	s_min_u32 s0, s0, 0xfc
	s_add_i32 s0, s0, 3
	v_mfma_f32_16x16x32_bf16 v[124:127], v[124:127], v[136:139], v[128:131]
	s_mul_i32 s8, s0, 0xe000
	s_add_u32 s48, s10, s8
	s_addc_u32 s49, s11, 0
	v_pk_mul_f32 v[130:131], v[170:171], v[244:245] op_sel_hi:[1,0]
	v_pk_mul_f32 v[128:129], v[168:169], v[244:245] op_sel_hi:[1,0]
	s_waitcnt lgkmcnt(0)
	v_mfma_f32_16x16x32_bf16 v[168:171], v[120:123], v[132:135], v[124:127]
	v_lshl_add_u64 v[120:121], s[48:49], 0, v[184:185]
	global_load_dwordx4 v[160:163], v[120:121], off
	global_load_dwordx4 v[164:167], v[120:121], off offset:1024
	global_load_dwordx4 v[156:159], v[120:121], off offset:2048
	global_load_dwordx4 v[152:155], v[120:121], off offset:3072
	s_lshl_b32 s0, s0, 14
	v_mfma_f32_16x16x32_bf16 v[96:99], v[96:99], v[136:139], v[128:131]
	v_lshl_add_u64 v[180:181], v[192:193], 0, s[0:1]
	v_add_u32_e32 v225, v215, v225
	v_cvt_pk_bf16_f32 v176, v176, s0
	v_mfma_f32_16x16x32_bf16 v[172:175], v[92:95], v[132:135], v[96:99]
	v_add_co_u32_e64 v94, s[8:9], s50, v120
	v_lshl_add_u64 v[92:93], v[120:121], 0, s[12:13]
	s_nop 0
	v_addc_co_u32_e64 v95, s[8:9], 0, v121, s[8:9]
	global_load_dwordx4 v[144:147], v[92:93], off offset:1024
	global_load_dwordx4 v[136:139], v[92:93], off offset:2048
	global_load_dwordx4 v[148:151], v[94:95], off
	global_load_dwordx4 v[132:135], v[92:93], off offset:3072
	v_lshl_add_u64 v[92:93], s[48:49], 0, v[188:189]
	v_add_co_u32_e64 v94, s[8:9], s51, v120
	global_load_dwordx4 v[140:143], v[92:93], off
	global_load_dwordx4 v[128:131], v[92:93], off offset:1024
	v_lshl_add_u64 v[92:93], v[120:121], 0, s[14:15]
	v_addc_co_u32_e64 v95, s[8:9], 0, v121, s[8:9]
	global_load_dwordx4 v[120:123], v[92:93], off offset:1024
	global_load_dwordx4 v[96:99], v[92:93], off offset:2048
	global_load_dwordx4 v[124:127], v[94:95], off
	s_nop 0
	global_load_dwordx4 v[92:95], v[92:93], off offset:3072
	v_cvt_pk_bf16_f32 v182, v172, v173
	global_load_dwordx2 v[208:209], v[180:181], off
	global_load_dword v244, v224, s[98:99] offset:20
	v_cvt_pk_bf16_f32 v180, v168, v169
	v_cvt_pk_bf16_f32 v181, v170, v171
	v_cvt_pk_bf16_f32 v183, v174, v175
	ds_write_b128 v225, v[180:183]
	v_add_co_u32_e64 v182, s[8:9], s60, v212
	v_lshl_add_u64 v[180:181], v[210:211], 0, s[40:41]
	s_nop 0
	v_addc_co_u32_e64 v183, s[8:9], 0, v213, s[8:9]
	global_store_short v[182:183], v176, off
	v_cvt_pk_bf16_f32 v182, v177, s0
	v_or_b32_e32 v176, 0x800, v180
	v_mov_b32_e32 v177, v181
	s_add_u32 s46, s46, 0x2a000
	v_lshl_add_u64 v[176:177], v[190:191], 0, v[176:177]
	s_addc_u32 s47, s47, 0
	global_store_short v[176:177], v182, off
	v_or_b32_e32 v176, 0x1000, v180
	v_mov_b32_e32 v177, v181
	s_add_u32 s18, s18, 12
	v_cvt_pk_bf16_f32 v178, v178, s0
	v_lshl_add_u64 v[176:177], v[190:191], 0, v[176:177]
	v_or_b32_e32 v180, 0x1800, v180
	s_addc_u32 s19, s19, 0
	global_store_short v[176:177], v178, off
	v_cvt_pk_bf16_f32 v178, v179, s0
	v_lshl_add_u64 v[176:177], v[190:191], 0, v[180:181]
	v_lshl_add_u64 v[198:199], v[198:199], 0, s[42:43]
	v_lshl_add_u64 v[196:197], v[196:197], 0, s[42:43]
	v_lshl_add_u64 v[200:201], v[200:201], 0, s[42:43]
	s_cmpk_gt_u32 s63, 0xfb
	v_lshl_add_u64 v[204:205], v[204:205], 0, s[44:45]
	global_store_short v[176:177], v178, off
	s_waitcnt lgkmcnt(0)
	s_barrier
	s_cbranch_scc1 .LBB0_884
	s_mov_b32 s61, s63
	s_branch .LBB0_874
.LBB0_884:
	s_waitcnt vmcnt(0)
	ds_read_b128 v[56:59], v215 offset:4096
	ds_read_b128 v[60:63], v215 offset:5120
	ds_read_b128 v[64:67], v215 offset:6144
	s_lshl_b64 s[0:1], s[4:5], 2
	s_add_u32 s0, s54, s0
	s_waitcnt lgkmcnt(2)
	v_mfma_f32_16x16x32_bf16 v[52:55], v[52:55], v[56:59], 0
	v_mov_b32_e32 v68, 0x319000
	s_addc_u32 s1, s55, s1
	s_waitcnt lgkmcnt(1)
	v_mfma_f32_16x16x32_bf16 v[48:51], v[48:51], v[60:63], v[52:55]
	s_waitcnt lgkmcnt(0)
	v_mfma_f32_16x16x32_bf16 v[46:49], v[44:47], v[64:67], v[48:51]
	global_load_dword v44, v68, s[0:1] offset:1020
	s_nop 0
	ds_read_b128 v[52:55], v215 offset:7168
	v_mfma_f32_16x16x32_bf16 v[36:39], v[36:39], v[56:59], 0
	v_mfma_f32_16x16x32_bf16 v[32:35], v[32:35], v[60:63], v[36:39]
	s_waitcnt lgkmcnt(0)
	v_mfma_f32_16x16x32_bf16 v[40:43], v[40:43], v[52:55], v[46:49]
	s_nop 4
	v_add3_u32 v36, v215, v221, v222
	v_lshlrev_b32_e32 v46, 16, v194
	v_and_b32_e32 v47, 0xffff0000, v194
	v_mfma_f32_16x16x32_bf16 v[28:31], v[28:31], v[64:67], v[32:35]
	v_add_f32_e64 v40, v46, -v40
	v_add_f32_e64 v41, v47, -v41
	v_lshlrev_b32_e32 v46, 16, v195
	v_and_b32_e32 v47, 0xffff0000, v195
	v_pk_add_f32 v[42:43], v[46:47], v[42:43] neg_lo:[0,1] neg_hi:[0,1]
	v_cvt_pk_bf16_f32 v40, v40, v41
	v_cvt_pk_bf16_f32 v41, v42, v43
	ds_write_b64 v36, v[40:41] offset:10240
	s_waitcnt lgkmcnt(0)
	s_barrier
	v_mfma_f32_16x16x32_bf16 v[20:23], v[20:23], v[52:55], v[28:31]
	ds_read_b128 v[32:35], v215 offset:10240
	s_nop 1
	ds_read_b128 v[28:31], v215 offset:11264
	s_waitcnt lgkmcnt(1)
	v_mfma_f32_16x16x32_bf16 v[20:23], v[24:27], v[32:35], v[20:23]
	s_and_saveexec_b64 s[0:1], vcc
	s_xor_b64 s[0:1], exec, s[0:1]
	s_andn2_saveexec_b64 s[0:1], s[0:1]
	s_cbranch_execz .LBB0_886
	s_waitcnt lgkmcnt(0)
	v_mfma_f32_16x16x32_bf16 v[20:23], v[16:19], v[28:31], v[20:23]
